# v31 + attention loop QK section software-pipelined: K fragments prefetched two key tiles ahead into unused VGPRs, counted lgkmcnt waits
# speedup vs baseline: 1.0404x; 1.0015x over previous
; __device__ __forceinline__ void phase_attention(const Params& p, int half, unsigned char* lds) {
;     ...
;             {
;                 bf16x8 qf[4];
; #pragma unroll
;                 for (int kk = 0; kk < 4; ++kk) qf[kk] = *(const bf16x8*)(Qs + (qt * 16 + fr) * QS + kk * 32 + fq * 8);
; #pragma unroll
;                 for (int k6 = 0; k6 < 6; ++k6) {
;                     f32x4 a = {0.f, 0.f, 0.f, 0.f};
;                     const int kt = kh * 6 + k6;
;                     int slot = sl0 + (kt >> 2); slot = (slot >= 3) ? slot - 3 : slot;
;                     const bf16_t* kr = Ks + (slot * 64 + (kt & 3) * 16 + fr) * QS + fq * 8;
; #pragma unroll
;                     for (int kk = 0; kk < 4; ++kk) {
;                         const bf16x8 kf = *(const bf16x8*)(kr + kk * 32);
;                         a = __builtin_amdgcn_mfma_f32_16x16x32_bf16(kf, qf[kk], a, 0, 0, 0);
;                     }
;                     s[k6] = a;
;                 }
;             }
.LBB0_181:
	s_mul_hi_i32 s2, s62, 0x55555556
	s_lshr_b32 s16, s2, 31
	s_add_i32 s2, s2, s16
	s_mul_i32 s2, s2, 3
	s_sub_i32 s2, s62, s2
	ds_read_b128 v[68:71], v89
	ds_read_b128 v[64:67], v89 offset:64
	ds_read_b128 v[60:63], v89 offset:128
	ds_read_b128 v[56:59], v89 offset:192
	v_add_u32_e32 v72, s2, v143
	v_cmp_lt_i32_e32 vcc, 2, v72
	v_lshlrev_b32_e32 v72, 6, v72
	v_add_u32_e32 v73, 0xffffff40, v72
	v_cndmask_b32_e32 v105, v72, v73, vcc
	v_or_b32_e32 v72, v105, v151
	v_mad_u32_u24 v232, v72, s73, v90
	v_or_b32_e32 v72, v105, v152
	v_mad_u32_u24 v233, v72, s73, v90
	ds_read_b128 v[208:211], v232 offset:17408
	ds_read_b128 v[212:215], v232 offset:17472
	ds_read_b128 v[216:219], v232 offset:17536
	ds_read_b128 v[220:223], v232 offset:17600
	ds_read_b128 v[224:227], v233 offset:17408
	ds_read_b128 v[228:231], v233 offset:17472
	ds_read_b128 v[240:243], v233 offset:17536
	ds_read_b128 v[244:247], v233 offset:17600
	v_add_u32_e32 v72, s2, v144
	v_cmp_lt_i32_e32 vcc, 2, v72
	v_lshlrev_b32_e32 v72, 6, v72
	v_add_u32_e32 v73, 0xffffff40, v72
	v_cndmask_b32_e32 v72, v72, v73, vcc
	v_or_b32_e32 v72, v72, v153
	v_mad_u32_u24 v234, v72, s73, v90
	v_add_u32_e32 v72, s2, v145
	v_cmp_lt_i32_e32 vcc, 2, v72
	v_lshlrev_b32_e32 v72, 6, v72
	v_add_u32_e32 v73, 0xffffff40, v72
	v_cndmask_b32_e32 v72, v72, v73, vcc
	v_or_b32_e32 v72, v72, v154
	v_mad_u32_u24 v239, v72, s73, v90
	v_add_u32_e32 v72, s2, v146
	v_cmp_lt_i32_e32 vcc, 2, v72
	v_lshlrev_b32_e32 v72, 6, v72
	v_add_u32_e32 v73, 0xffffff40, v72
	v_cndmask_b32_e32 v72, v72, v73, vcc
	v_or_b32_e32 v72, v72, v155
	v_mad_u32_u24 v248, v72, s73, v90
	v_add_u32_e32 v72, s2, v147
	v_cmp_lt_i32_e32 vcc, 2, v72
	v_lshlrev_b32_e32 v72, 6, v72
	v_add_u32_e32 v73, 0xffffff40, v72
	v_cndmask_b32_e32 v72, v72, v73, vcc
	v_or_b32_e32 v72, v72, v156
	v_mad_u32_u24 v249, v72, s73, v90
	s_add_i32 s3, s65, s62
	s_cmp_eq_u32 s62, 2
	s_cselect_b64 s[16:17], -1, 0
	s_cmp_eq_u32 s3, 2
	s_cselect_b64 s[30:31], -1, 0
	s_and_b64 s[34:35], s[16:17], s[6:7]
	s_and_b64 s[78:79], s[30:31], s[8:9]
	s_or_b64 vcc, s[34:35], s[78:79]
	s_and_b64 s[88:89], s[16:17], s[10:11]
	s_and_b64 s[30:31], s[30:31], s[12:13]
	s_waitcnt lgkmcnt(4)
	v_mfma_f32_16x16x32_bf16 v[72:75], v[208:211], v[68:71], 0
	v_mfma_f32_16x16x32_bf16 v[72:75], v[212:215], v[64:67], v[72:75]
	v_mfma_f32_16x16x32_bf16 v[72:75], v[216:219], v[60:63], v[72:75]
	v_mfma_f32_16x16x32_bf16 v[72:75], v[220:223], v[56:59], v[72:75]
	ds_read_b128 v[208:211], v234 offset:17408
	ds_read_b128 v[212:215], v234 offset:17472
	ds_read_b128 v[216:219], v234 offset:17536
	ds_read_b128 v[220:223], v234 offset:17600
	s_waitcnt lgkmcnt(4)
	v_mfma_f32_16x16x32_bf16 v[160:163], v[224:227], v[68:71], 0
	v_mfma_f32_16x16x32_bf16 v[160:163], v[228:231], v[64:67], v[160:163]
	v_mfma_f32_16x16x32_bf16 v[160:163], v[240:243], v[60:63], v[160:163]
	v_mfma_f32_16x16x32_bf16 v[160:163], v[244:247], v[56:59], v[160:163]
	ds_read_b128 v[224:227], v239 offset:17408
	ds_read_b128 v[228:231], v239 offset:17472
	ds_read_b128 v[240:243], v239 offset:17536
	ds_read_b128 v[244:247], v239 offset:17600
	s_waitcnt lgkmcnt(4)
	v_mfma_f32_16x16x32_bf16 v[188:191], v[208:211], v[68:71], 0
	v_mfma_f32_16x16x32_bf16 v[188:191], v[212:215], v[64:67], v[188:191]
	v_mfma_f32_16x16x32_bf16 v[188:191], v[216:219], v[60:63], v[188:191]
	v_mfma_f32_16x16x32_bf16 v[188:191], v[220:223], v[56:59], v[188:191]
	ds_read_b128 v[208:211], v248 offset:17408
	ds_read_b128 v[212:215], v248 offset:17472
	ds_read_b128 v[216:219], v248 offset:17536
	ds_read_b128 v[220:223], v248 offset:17600
	s_waitcnt lgkmcnt(4)
	v_mfma_f32_16x16x32_bf16 v[192:195], v[224:227], v[68:71], 0
	v_mfma_f32_16x16x32_bf16 v[192:195], v[228:231], v[64:67], v[192:195]
	v_mfma_f32_16x16x32_bf16 v[192:195], v[240:243], v[60:63], v[192:195]
	v_mfma_f32_16x16x32_bf16 v[192:195], v[244:247], v[56:59], v[192:195]
	ds_read_b128 v[224:227], v249 offset:17408
	ds_read_b128 v[228:231], v249 offset:17472
	ds_read_b128 v[240:243], v249 offset:17536
	ds_read_b128 v[244:247], v249 offset:17600
	s_waitcnt lgkmcnt(4)
; __device__ __forceinline__ void phase_attention(const Params& p, int half, unsigned char* lds) {
;     ...
;                     for (int kk = 0; kk < 4; ++kk) {
;                         const bf16x8 kf = *(const bf16x8*)(kr + kk * 32);
;                         a = __builtin_amdgcn_mfma_f32_16x16x32_bf16(kf, qf[kk], a, 0, 0, 0);
;                     }
;                     s[k6] = a;
;                 }
;             }
;             const int qi = qt * 16 + fr;
;             float mx = -3.0e38f;
;             const bool lo_bad = (b == 0), hi_bad = (b == nb - 1);
; #pragma unroll
;             for (int k6 = 0; k6 < 6; ++k6) {
;                 const int kt = kh * 6 + k6;
;                 const bool blk_bad = (lo_bad && kt < 4) || (hi_bad && kt >= 8);
; #pragma unroll
;                 for (int jj = 0; jj < 4; ++jj) {
;                     const float v = blk_bad ? -1.0e30f : (s[k6][jj] * sc + madd[k6][jj]);
;                     s[k6][jj] = v; mx = fmaxf(mx, v);
;                 }
;             }
;             mx = fmaxf(mx, __shfl_xor(mx, 16)); mx = fmaxf(mx, __shfl_xor(mx, 32));
;             if (fq == 0) red[kh * 64 + qi] = mx;
	v_mfma_f32_16x16x32_bf16 v[196:199], v[208:211], v[68:71], 0
	v_mfma_f32_16x16x32_bf16 v[196:199], v[212:215], v[64:67], v[196:199]
	v_mfma_f32_16x16x32_bf16 v[196:199], v[216:219], v[60:63], v[196:199]
	v_mfma_f32_16x16x32_bf16 v[196:199], v[220:223], v[56:59], v[196:199]
	s_waitcnt lgkmcnt(0)
	v_mfma_f32_16x16x32_bf16 v[200:203], v[224:227], v[68:71], 0
	v_mfma_f32_16x16x32_bf16 v[200:203], v[228:231], v[64:67], v[200:203]
	v_mfma_f32_16x16x32_bf16 v[200:203], v[240:243], v[60:63], v[200:203]
	v_mfma_f32_16x16x32_bf16 v[200:203], v[244:247], v[56:59], v[200:203]
	v_fmamk_f32 v56, v72, 0x3e0293ee, v83
	v_fmamk_f32 v57, v74, 0x3e0293ee, v87
	v_cndmask_b32_e32 v186, v56, v164, vcc
	v_fmamk_f32 v56, v73, 0x3e0293ee, v85
	v_cndmask_b32_e32 v184, v57, v164, vcc
	v_fmamk_f32 v57, v75, 0x3e0293ee, v91
	v_cndmask_b32_e32 v185, v56, v164, vcc
	v_cndmask_b32_e32 v183, v57, v164, vcc
	s_or_b64 vcc, s[88:89], s[78:79]
	v_fmamk_f32 v57, v160, 0x3e0293ee, v114
	v_cndmask_b32_e32 v132, v57, v164, vcc
	v_fmamk_f32 v57, v161, 0x3e0293ee, v115
	v_cndmask_b32_e32 v105, v57, v164, vcc
	v_fmamk_f32 v57, v162, 0x3e0293ee, v116
	v_cndmask_b32_e32 v75, v57, v164, vcc
	v_fmamk_f32 v57, v163, 0x3e0293ee, v117
	v_cndmask_b32_e32 v74, v57, v164, vcc
	s_or_b64 vcc, s[34:35], s[30:31]
	v_fmamk_f32 v57, v188, 0x3e0293ee, v118
	v_cndmask_b32_e32 v73, v57, v164, vcc
	v_fmamk_f32 v57, v189, 0x3e0293ee, v119
	v_cndmask_b32_e32 v72, v57, v164, vcc
	v_fmamk_f32 v57, v190, 0x3e0293ee, v120
	v_cndmask_b32_e32 v71, v57, v164, vcc
	v_fmamk_f32 v57, v191, 0x3e0293ee, v121
	v_cndmask_b32_e32 v70, v57, v164, vcc
	v_fmamk_f32 v57, v192, 0x3e0293ee, v122
	v_max3_f32 v56, v186, s74, v185
	v_cndmask_b32_e32 v69, v57, v164, vcc
	v_fmamk_f32 v57, v193, 0x3e0293ee, v123
	v_max3_f32 v56, v56, v184, v183
	v_cndmask_b32_e32 v68, v57, v164, vcc
	v_fmamk_f32 v57, v194, 0x3e0293ee, v124
	v_max3_f32 v56, v56, v132, v105
	v_cndmask_b32_e32 v65, v57, v164, vcc
	v_fmamk_f32 v57, v195, 0x3e0293ee, v125
	s_and_b64 s[16:17], s[16:17], s[14:15]
	v_max3_f32 v56, v56, v75, v74
	v_cndmask_b32_e32 v64, v57, v164, vcc
	s_or_b64 vcc, s[16:17], s[30:31]
	v_fmamk_f32 v57, v196, 0x3e0293ee, v126
	v_max3_f32 v56, v56, v73, v72
	v_cndmask_b32_e32 v63, v57, v164, vcc
	v_fmamk_f32 v57, v197, 0x3e0293ee, v127
	v_max3_f32 v56, v56, v71, v70
	v_cndmask_b32_e32 v62, v57, v164, vcc
	v_fmamk_f32 v57, v198, 0x3e0293ee, v128
	v_max3_f32 v56, v56, v69, v68
	v_cndmask_b32_e32 v61, v57, v164, vcc
	v_fmamk_f32 v57, v199, 0x3e0293ee, v129
	v_max3_f32 v56, v56, v65, v64
	v_cndmask_b32_e32 v60, v57, v164, vcc
	v_fmamk_f32 v57, v200, 0x3e0293ee, v130
	v_max3_f32 v56, v56, v63, v62
	v_cndmask_b32_e32 v59, v57, v164, vcc
	v_fmamk_f32 v57, v201, 0x3e0293ee, v131
	v_max3_f32 v56, v56, v61, v60
	v_cndmask_b32_e32 v58, v57, v164, vcc
	v_max3_f32 v66, v56, v59, v58
	v_fmamk_f32 v56, v202, 0x3e0293ee, v134
	v_cndmask_b32_e32 v57, v56, v164, vcc
	v_fmamk_f32 v56, v203, 0x3e0293ee, v136
	v_cndmask_b32_e32 v56, v56, v164, vcc
	v_and_b32_e32 v160, 64, v166
	v_max3_f32 v67, v66, v57, v56
	v_xor_b32_e32 v66, 16, v166
	v_add_u32_e32 v160, 64, v160
	v_cmp_lt_i32_e32 vcc, v66, v160
	s_nop 1
	v_cndmask_b32_e32 v66, v166, v66, vcc
	v_lshlrev_b32_e32 v66, 2, v66
	ds_bpermute_b32 v161, v66, v67
	s_waitcnt lgkmcnt(0)
	v_max_f32_e32 v161, v161, v161
	v_max_f32_e32 v187, v67, v161
	v_xor_b32_e32 v67, 32, v166
	v_cmp_lt_i32_e32 vcc, v67, v160
	s_nop 1
	v_cndmask_b32_e32 v67, v166, v67, vcc
	v_lshlrev_b32_e32 v67, 2, v67
	ds_bpermute_b32 v188, v67, v187
	s_and_saveexec_b64 s[16:17], s[4:5]
	s_cbranch_execz .LBB0_183
	s_waitcnt lgkmcnt(0)
	v_max_f32_e32 v160, v188, v188
	v_max_f32_e32 v161, v187, v187
	v_max_f32_e32 v160, v161, v160
	ds_write_b32 v140, v160
